# differential attention: no row-maximum pass on the common path -- exponentials taken against the standing reference, row sum <= 256 proves every probability is in range, otherwise the tile is redone o
# speedup vs baseline: 1.0108x; 1.0059x over previous
; __device__ __forceinline__ void diff_attn_item(CParams& p, int j, int layer, LAS unsigned char* lds, int b, int h, int qb, int tid_in, int lane_in, int wave) {
;     ...
;     const int mp = wave >> 2, qs = wave & 3, r = lane & 31, hh = lane >> 5;
;     const int tb0 = b * SEQ; const int q0 = qb * 128 + 32 * qs;
;     if (tid < 129) bdl[tid] = bd[tid];
;     h16x8 qf[4];
; #pragma unroll
;     for (int s = 0; s < 4; ++s) qf[s] = *(const h16x8*)(proj + (size_t)(tb0 + q0 + r) * OD_N + h * 128 + mp * 64 + 16 * s + 8 * hh);
;     f32x16 o[4];
; #pragma unroll
;     for (int d = 0; d < 4; ++d)
; #pragma unroll
;         for (int i = 0; i < 16; ++i) o[d][i] = 0.f;
;     float m_run = -INFINITY, l_run = 0.f;
;     const int qp = q0 + r;
;     const int vlo = r * 72 + ((hh ^ (r >> 3)) << 2), vhi = r * 72 + (((hh ^ (r >> 3)) ^ 2) << 2);
;     const int nkt = 2 * (qb + 1);
;     h16x8 pk[2], pv[2];
; #pragma unroll
;     for (int i = 0; i < 2; ++i) { const int key = i * 32 + (tid >> 4), ch = tid & 15;
;         pk[i] = *(const h16x8*)(proj + (size_t)(tb0 + key) * OD_N + 512 + h * 128 + ch * 8);
;         pv[i] = *(const h16x8*)(proj + (size_t)(tb0 + key) * OD_N + 1024 + h * 128 + ch * 8); }
;     ...
;     ATT_STAGE(0, 512 + h * 128, 1024 + h * 128, 1);
;     __syncthreads();
.LBB0_597:
	s_or_b64 exec, exec, s[4:5]
	s_mov_b32 s100, 0
	s_lshl_b32 s4, s35, 2
	s_and_b32 s4, s4, 24
	s_add_i32 s4, s4, s73
	s_and_b32 s4, s4, 31
	s_and_b32 s5, s35, 1
	s_xor_b32 s6, s4, 31
	s_cmp_eq_u32 s5, 0
	s_cselect_b32 s6, s4, s6
	s_lshl_b32 s4, s35, 10
	s_and_b32 s4, s4, 0x1000
	s_or_b32 s7, s4, s34
	v_ashrrev_i32_e32 v3, 4, v2
	v_add_u32_e32 v200, s7, v3
	v_lshlrev_b32_e32 v0, 4, v2
	s_lshl_b32 s30, s6, 7
	v_mov_b64_e32 v[20:21], s[14:15]
	v_and_b32_e32 v22, 0xf0, v0
	v_add_u32_e32 v0, 32, v200
	v_and_b32_e32 v198, 31, v2
	v_or_b32_e32 v199, s30, v186
	s_lshl_b32 s58, s12, 8
	v_mad_i64_i32 v[4:5], s[4:5], v200, s33, v[20:21]
	v_mad_i64_i32 v[12:13], s[4:5], v0, s33, v[20:21]
	s_lshl_b32 s36, s12, 7
	s_lshl_b32 s37, s6, 1
	v_or3_b32 v0, s7, v198, v199
	s_add_u32 s4, s14, s58
	v_mad_u64_u32 v[20:21], s[12:13], v0, s33, v[20:21]
	v_bfe_u32 v30, v2, 5, 1
	s_addc_u32 s5, s15, 0
	v_lshl_add_u64 v[20:21], v[20:21], 0, s[58:59]
	v_lshl_add_u64 v[4:5], v[4:5], 0, s[58:59]
	v_mov_b32_e32 v23, v1
	v_lshl_add_u64 v[12:13], v[12:13], 0, s[58:59]
	v_mov_b32_e32 v25, v1
	v_lshlrev_b32_e32 v24, 4, v30
	v_add_u32_e32 v28, 64, v200
	v_add_u32_e32 v31, 0x60, v200
	v_mov_b64_e32 v[26:27], s[4:5]
	v_lshl_add_u64 v[20:21], v[140:141], 1, v[20:21]
	v_lshl_add_u64 v[8:9], v[4:5], 0, v[22:23]
	v_lshl_add_u64 v[16:17], v[12:13], 0, v[22:23]
	v_mad_i64_i32 v[28:29], s[12:13], v28, s33, v[26:27]
	v_mad_i64_i32 v[26:27], s[12:13], v31, s33, v[26:27]
	v_lshl_add_u64 v[20:21], v[20:21], 0, v[24:25]
	global_load_dwordx4 v[4:7], v[8:9], off offset:1024
	s_nop 0
	global_load_dwordx4 v[8:11], v[8:9], off offset:2048
	s_nop 0
	global_load_dwordx4 v[12:15], v[16:17], off offset:1024
	s_nop 0
	global_load_dwordx4 v[16:19], v[16:17], off offset:2048
	v_lshl_add_u64 v[28:29], v[28:29], 0, v[22:23]
	v_lshl_add_u64 v[26:27], v[26:27], 0, v[22:23]
	global_load_dwordx4 v[110:113], v[20:21], off
	global_load_dwordx4 v[106:109], v[20:21], off offset:32
	global_load_dwordx4 v[102:105], v[20:21], off offset:64
	global_load_dwordx4 v[98:101], v[20:21], off offset:96
	global_load_dwordx4 v[126:129], v[28:29], off offset:1024
	global_load_dwordx4 v[118:121], v[28:29], off offset:2048
	global_load_dwordx4 v[122:125], v[26:27], off offset:1024
	global_load_dwordx4 v[114:117], v[26:27], off offset:2048
	v_and_b32_e32 v193, 63, v2
	v_bfe_u32 v20, v2, 3, 2
	v_and_b32_e32 v2, 15, v2
	v_lshlrev_b32_e32 v21, 2, v2
	v_lshlrev_b32_e32 v25, 1, v3
	v_lshl_add_u32 v202, v2, 4, 0
	v_mul_lo_u32 v203, v3, s97
	v_mul_u32_u24_e32 v204, 0x480, v2
	v_and_b32_e32 v25, 6, v25
	v_bfe_u32 v26, v3, 2, 1
	v_bfe_u32 v27, v3, 3, 1
	v_and_b32_e32 v2, -13, v3
	v_lshl_or_b32 v2, v26, 3, v2
	v_lshl_or_b32 v26, v27, 2, v2
	v_and_b32_e32 v21, 0x38, v21
	v_add_u32_e32 v2, 32, v26
	v_bitop3_b32 v3, v26, v21, -4 bitop3:0x6c
	v_bitop3_b32 v2, v2, v21, -4 bitop3:0x6c
	v_add_u32_e32 v205, 0, v25
	v_lshlrev_b32_e32 v206, 1, v3
	v_add_u32_e32 v27, v202, v203
	v_lshlrev_b32_e32 v207, 1, v2
	v_add3_u32 v2, v205, v206, v204
	v_xor_b32_e32 v20, v30, v20
	v_lshlrev_b32_e32 v26, 2, v20
	v_lshlrev_b32_e32 v192, 2, v30
	v_xor_b32_e32 v194, 8, v26
	v_add_u32_e32 v208, v187, v24
	v_bfe_u32 v196, v193, 4, 1
	v_xor_b32_e32 v196, v30, v196
	v_lshlrev_b32_e32 v196, 4, v196
	s_waitcnt vmcnt(29)
	v_lshl_add_u64 v[130:131], s[4:5], 0, v[22:23]
	v_mov_b32_e32 v3, v1
	s_mov_b32 s38, 0
	s_or_b32 s39, s37, 1
	v_or_b32_e32 v210, 31, v199
	v_mad_u32_u24 v195, v198, s60, 0
	v_mul_u32_u24_e32 v209, 0x110, v198
	v_mad_u32_u24 v211, v198, s97, v208
	v_mov_b32_e32 v197, 0
	v_mov_b32_e32 v201, 0xff800000
	s_movk_i32 s40, 0xbf
	s_waitcnt vmcnt(11)
	ds_write_b128 v27, v[4:7]
	s_waitcnt vmcnt(10)
	ds_write_b16 v2, v8 offset:34816
	ds_write_b16_d16_hi v2, v8 offset:34960
	ds_write_b16 v2, v9 offset:35104
	ds_write_b16_d16_hi v2, v9 offset:35248
	ds_write_b16 v2, v10 offset:35392
	ds_write_b16_d16_hi v2, v10 offset:35536
	ds_write_b16 v2, v11 offset:35680
	ds_write_b16_d16_hi v2, v11 offset:35824
	s_waitcnt vmcnt(9)
	ds_write_b128 v27, v[12:15] offset:8704
	v_add3_u32 v2, v205, v207, v204
	s_waitcnt vmcnt(8)
	ds_write_b16 v2, v16 offset:34816
	ds_write_b16_d16_hi v2, v16 offset:34960
	ds_write_b16 v2, v17 offset:35104
	ds_write_b16_d16_hi v2, v17 offset:35248
	ds_write_b16 v2, v18 offset:35392
	ds_write_b16_d16_hi v2, v18 offset:35536
	ds_write_b16 v2, v19 offset:35680
	ds_write_b16_d16_hi v2, v19 offset:35824
	v_add3_u32 v2, v191, s30, v198
	v_mov_b32_e32 v16, v1
	v_mov_b32_e32 v17, v1
	v_sub_u32_e32 v212, v2, v192
	v_mov_b32_e32 v2, v1
	v_mov_b32_e32 v4, v1
	v_mov_b32_e32 v5, v1
	v_mov_b32_e32 v6, v1
	v_mov_b32_e32 v7, v1
	v_mov_b32_e32 v8, v1
	v_mov_b32_e32 v9, v1
	v_mov_b32_e32 v10, v1
	v_mov_b32_e32 v11, v1
	v_mov_b32_e32 v12, v1
	v_mov_b32_e32 v13, v1
	v_mov_b32_e32 v14, v1
	v_mov_b32_e32 v15, v1
	v_mov_b64_e32 v[32:33], v[16:17]
	v_mov_b64_e32 v[48:49], v[16:17]
	v_mov_b64_e32 v[64:65], v[16:17]
	v_mov_b64_e32 v[30:31], v[14:15]
	v_mov_b64_e32 v[28:29], v[12:13]
	v_mov_b64_e32 v[26:27], v[10:11]
	v_mov_b64_e32 v[24:25], v[8:9]
	v_mov_b64_e32 v[22:23], v[6:7]
	v_mov_b64_e32 v[20:21], v[4:5]
	v_mov_b64_e32 v[18:19], v[2:3]
	v_mov_b64_e32 v[46:47], v[14:15]
	v_mov_b64_e32 v[44:45], v[12:13]
	v_mov_b64_e32 v[42:43], v[10:11]
	v_mov_b64_e32 v[40:41], v[8:9]
	v_mov_b64_e32 v[38:39], v[6:7]
	v_mov_b64_e32 v[36:37], v[4:5]
	v_mov_b64_e32 v[34:35], v[2:3]
	v_mov_b64_e32 v[62:63], v[14:15]
	v_mov_b64_e32 v[60:61], v[12:13]
	v_mov_b64_e32 v[58:59], v[10:11]
	v_mov_b64_e32 v[56:57], v[8:9]
	v_mov_b64_e32 v[54:55], v[6:7]
	v_mov_b64_e32 v[52:53], v[4:5]
	v_mov_b64_e32 v[50:51], v[2:3]
	s_waitcnt lgkmcnt(0)
	s_barrier
; #define LAS __attribute__((address_space(3)))
; __device__ __forceinline__ f32x16 mma32(const h16x8 a, const h16x8 b, const f32x16 c) { return __builtin_amdgcn_mfma_f32_32x32x16_f16(a, b, c, 0, 0, 0); }
; __device__ __forceinline__ void diff_attn_item(CParams& p, int j, int layer, LAS unsigned char* lds, int b, int h, int qb, int tid_in, int lane_in, int wave) {
;     ...
;     for (int kt = 0; kt < nkt; ++kt) {
;         const int k0 = kt * 64; const int cur = kt & 1;
;         const LAS h16* Ks = Ks0 + cur * 8704; const LAS h16* Vt = Vt0 + cur * 9216;
;         if (kt + 1 < nkt) ATT_STAGE(cur ^ 1, 512 + h * 128, 1024 + h * 128, kt + 2);
;         if (!(k0 > q0 + 31)) {
;         f32x16 sc[2];
; #pragma unroll
;         for (int sub = 0; sub < 2; ++sub) {
; #pragma unroll
;             for (int i = 0; i < 16; ++i) sc[sub][i] = 0.f;
; #pragma unroll
;             for (int s = 0; s < 4; ++s) sc[sub] = mma32(*(const LAS h16x8*)(Ks + (32 * sub + r) * 136 + mp * 64 + 16 * s + 8 * hh), qf[s], sc[sub]);
;         }
;         float mx = -INFINITY;
;         if (k0 + 63 + 128 <= q0) {
;             const float bfar = bdl[128];
; #pragma unroll
;             for (int sub = 0; sub < 2; ++sub)
; #pragma unroll
;                 for (int i = 0; i < 16; ++i) { sc[sub][i] += bfar; mx = fmaxf(mx, sc[sub][i]); }
;         } else {
; #pragma unroll
;             for (int sub = 0; sub < 2; ++sub)
; #pragma unroll
;                 for (int i = 0; i < 16; ++i) { const int kp = k0 + 32 * sub + (i & 3) + 8 * (i >> 2) + 4 * hh; const int dist = qp - kp;
;                     const float v = dist < 0 ? -INFINITY : sc[sub][i] + bdl[dist < 128 ? dist : 128]; sc[sub][i] = v; mx = fmaxf(mx, v); }
.LBB0_598:
	s_and_b32 s41, s38, 1
	s_xor_b32 s4, s41, 1
	s_mul_i32 s5, s4, 0x4400
	s_mulk_i32 s4, 0x4800
	s_add_i32 s6, s40, 0xffffff41
	v_add_u32_e32 v66, s4, v205
	s_add_i32 s4, s38, 2
	s_cmp_lt_u32 s38, s37
	v_add3_u32 v67, v202, s5, v203
	v_add3_u32 v68, v66, v206, v204
	s_cselect_b32 s4, s4, s39
	s_waitcnt vmcnt(3)
	ds_write_b128 v67, v[126:129]
	s_waitcnt vmcnt(2)
	ds_write_b16 v68, v118 offset:34816
	ds_write_b16_d16_hi v68, v118 offset:34960
	ds_write_b16 v68, v119 offset:35104
	ds_write_b16_d16_hi v68, v119 offset:35248
	ds_write_b16 v68, v120 offset:35392
	ds_write_b16_d16_hi v68, v120 offset:35536
	ds_write_b16 v68, v121 offset:35680
	ds_write_b16_d16_hi v68, v121 offset:35824
	s_waitcnt vmcnt(1)
	ds_write_b128 v67, v[122:125] offset:8704
	v_add3_u32 v66, v66, v207, v204
	v_lshl_add_u32 v68, s4, 6, v200
	s_waitcnt vmcnt(0)
	ds_write_b16 v66, v114 offset:34816
	ds_write_b16_d16_hi v66, v114 offset:34960
	ds_write_b16 v66, v115 offset:35104
	ds_write_b16_d16_hi v66, v115 offset:35248
	ds_write_b16 v66, v116 offset:35392
	ds_write_b16_d16_hi v66, v116 offset:35536
	ds_write_b16 v66, v117 offset:35680
	ds_write_b16_d16_hi v66, v117 offset:35824
	v_mad_i64_i32 v[66:67], s[4:5], v68, s33, v[130:131]
	global_load_dwordx4 v[126:129], v[66:67], off offset:1024
	global_load_dwordx4 v[118:121], v[66:67], off offset:2048
	v_add_u32_e32 v66, 32, v68
	v_mad_i64_i32 v[66:67], s[4:5], v66, s33, v[130:131]
	global_load_dwordx4 v[122:125], v[66:67], off offset:1024
	global_load_dwordx4 v[114:117], v[66:67], off offset:2048
	v_cmp_le_u32_e32 vcc, s6, v210
	s_and_saveexec_b64 s[4:5], vcc
	s_cbranch_execz .LBB0_670
	s_mov_b32 s101, 0
.LdiffA_top:
	s_mul_i32 s6, s41, 0x4400
	v_add_u32_e32 v214, s6, v211
	ds_read_b128 v[66:69], v214 offset:0
	ds_read_b128 v[70:73], v214 offset:32
	ds_read_b128 v[74:77], v214 offset:64
	ds_read_b128 v[78:81], v214 offset:96
	ds_read_b128 v[82:85], v214 offset:8704
	ds_read_b128 v[86:89], v214 offset:8736
	ds_read_b128 v[90:93], v214 offset:8768
	ds_read_b128 v[94:97], v214 offset:8800
	s_mul_i32 s12, s41, 0x4800
	v_add3_u32 v215, v195, v196, s12
	v_readfirstlane_b32 s6, v199
	s_mov_b32 s7, 0x11800
	s_waitcnt lgkmcnt(4)
	v_mfma_f32_32x32x16_f16 v[162:177], v[66:69], v[110:113], 0
	v_mfma_f32_32x32x16_f16 v[162:177], v[70:73], v[106:109], v[162:177]
	v_mfma_f32_32x32x16_f16 v[162:177], v[74:77], v[102:105], v[162:177]
	v_mfma_f32_32x32x16_f16 v[162:177], v[78:81], v[98:101], v[162:177]
	s_waitcnt lgkmcnt(0)
	v_mfma_f32_32x32x16_f16 v[228:243], v[82:85], v[110:113], 0
	v_mfma_f32_32x32x16_f16 v[228:243], v[86:89], v[106:109], v[228:243]
	v_mfma_f32_32x32x16_f16 v[228:243], v[90:93], v[102:105], v[228:243]
	v_mfma_f32_32x32x16_f16 v[228:243], v[94:97], v[98:101], v[228:243]
	s_sub_u32 s6, s6, s40
	s_add_u32 s6, s6, 0xbf
	s_cmp_ge_i32 s6, 0xbf
	s_cbranch_scc1 .LdiffA_far
	s_andn2_b32 s12, s6, 32
	s_cmp_eq_u32 s12, 64
	s_cbranch_scc1 .LdiffA_mid
	s_movk_i32 s12, 0x80
	v_add_u32_e32 v66, 59, v212
	v_med3_i32 v66, v66, 0, s12
	v_lshl_add_u32 v66, v66, 2, s7
	ds_read_b32 v66, v66
	v_add_u32_e32 v67, 58, v212
	v_med3_i32 v67, v67, 0, s12
	v_lshl_add_u32 v67, v67, 2, s7
	ds_read_b32 v67, v67
	v_add_u32_e32 v68, 57, v212
	v_med3_i32 v68, v68, 0, s12
	v_lshl_add_u32 v68, v68, 2, s7
	ds_read_b32 v68, v68
	v_add_u32_e32 v69, 56, v212
	v_med3_i32 v69, v69, 0, s12
	v_lshl_add_u32 v69, v69, 2, s7
	ds_read_b32 v69, v69
	v_add_u32_e32 v70, 51, v212
	v_med3_i32 v70, v70, 0, s12
	v_lshl_add_u32 v70, v70, 2, s7
	ds_read_b32 v70, v70
	v_add_u32_e32 v71, 50, v212
	v_med3_i32 v71, v71, 0, s12
	v_lshl_add_u32 v71, v71, 2, s7
	ds_read_b32 v71, v71
	v_add_u32_e32 v72, 49, v212
	v_med3_i32 v72, v72, 0, s12
	v_lshl_add_u32 v72, v72, 2, s7
	ds_read_b32 v72, v72
	v_add_u32_e32 v73, 48, v212
	v_med3_i32 v73, v73, 0, s12
	v_lshl_add_u32 v73, v73, 2, s7
	ds_read_b32 v73, v73
	v_add_u32_e32 v74, 43, v212
	v_med3_i32 v74, v74, 0, s12
	v_lshl_add_u32 v74, v74, 2, s7
	ds_read_b32 v74, v74
	v_add_u32_e32 v75, 42, v212
	v_med3_i32 v75, v75, 0, s12
	v_lshl_add_u32 v75, v75, 2, s7
	ds_read_b32 v75, v75
	v_add_u32_e32 v76, 41, v212
	v_med3_i32 v76, v76, 0, s12
	v_lshl_add_u32 v76, v76, 2, s7
	ds_read_b32 v76, v76
	v_add_u32_e32 v77, 40, v212
	v_med3_i32 v77, v77, 0, s12
	v_lshl_add_u32 v77, v77, 2, s7
	ds_read_b32 v77, v77
	v_add_u32_e32 v78, 35, v212
	v_med3_i32 v78, v78, 0, s12
	v_lshl_add_u32 v78, v78, 2, s7
	ds_read_b32 v78, v78
	v_add_u32_e32 v79, 34, v212
	v_med3_i32 v79, v79, 0, s12
	v_lshl_add_u32 v79, v79, 2, s7
	ds_read_b32 v79, v79
	v_add_u32_e32 v80, 33, v212
	v_med3_i32 v80, v80, 0, s12
	v_lshl_add_u32 v80, v80, 2, s7
	ds_read_b32 v80, v80
	v_add_u32_e32 v81, 32, v212
	v_med3_i32 v81, v81, 0, s12
	v_lshl_add_u32 v81, v81, 2, s7
	ds_read_b32 v81, v81
	v_add_u32_e32 v82, 27, v212
	v_med3_i32 v82, v82, 0, s12
	v_lshl_add_u32 v82, v82, 2, s7
	ds_read_b32 v82, v82
	v_add_u32_e32 v83, 26, v212
	v_med3_i32 v83, v83, 0, s12
	v_lshl_add_u32 v83, v83, 2, s7
	ds_read_b32 v83, v83
	v_add_u32_e32 v84, 25, v212
	v_med3_i32 v84, v84, 0, s12
	v_lshl_add_u32 v84, v84, 2, s7
	ds_read_b32 v84, v84
	v_add_u32_e32 v85, 24, v212
	v_med3_i32 v85, v85, 0, s12
	v_lshl_add_u32 v85, v85, 2, s7
	ds_read_b32 v85, v85
	v_add_u32_e32 v86, 19, v212
	v_med3_i32 v86, v86, 0, s12
	v_lshl_add_u32 v86, v86, 2, s7
	ds_read_b32 v86, v86
	v_add_u32_e32 v87, 18, v212
	v_med3_i32 v87, v87, 0, s12
	v_lshl_add_u32 v87, v87, 2, s7
	ds_read_b32 v87, v87
	v_add_u32_e32 v88, 17, v212
	v_med3_i32 v88, v88, 0, s12
	v_lshl_add_u32 v88, v88, 2, s7
	ds_read_b32 v88, v88
	v_add_u32_e32 v89, 16, v212
	v_med3_i32 v89, v89, 0, s12
	v_lshl_add_u32 v89, v89, 2, s7
	ds_read_b32 v89, v89
	v_add_u32_e32 v90, 11, v212
	v_med3_i32 v90, v90, 0, s12
	v_lshl_add_u32 v90, v90, 2, s7
	ds_read_b32 v90, v90
	v_add_u32_e32 v91, 10, v212
	v_med3_i32 v91, v91, 0, s12
	v_lshl_add_u32 v91, v91, 2, s7
	ds_read_b32 v91, v91
	v_add_u32_e32 v92, 9, v212
	v_med3_i32 v92, v92, 0, s12
	v_lshl_add_u32 v92, v92, 2, s7
	ds_read_b32 v92, v92
	v_add_u32_e32 v93, 8, v212
	v_med3_i32 v93, v93, 0, s12
	v_lshl_add_u32 v93, v93, 2, s7
	ds_read_b32 v93, v93
	v_add_u32_e32 v94, 3, v212
	v_med3_i32 v94, v94, 0, s12
	v_lshl_add_u32 v94, v94, 2, s7
	ds_read_b32 v94, v94
	v_add_u32_e32 v95, 2, v212
	v_med3_i32 v95, v95, 0, s12
	v_lshl_add_u32 v95, v95, 2, s7
	ds_read_b32 v95, v95
	v_add_u32_e32 v96, 1, v212
	v_med3_i32 v96, v96, 0, s12
	v_lshl_add_u32 v96, v96, 2, s7
	ds_read_b32 v96, v96
	v_add_u32_e32 v97, 0, v212
	v_med3_i32 v97, v97, 0, s12
	v_lshl_add_u32 v97, v97, 2, s7
	ds_read_b32 v97, v97
	v_sub_u32_e32 v145, 0, v212
	v_mov_b32_e32 v144, 0xff800000
	s_nop 4
	s_waitcnt lgkmcnt(0)
; __device__ __forceinline__ void diff_attn_item(CParams& p, int j, int layer, LAS unsigned char* lds, int b, int h, int qb, int tid_in, int lane_in, int wave) {
;     ...
;         } else {
; #pragma unroll
;             for (int sub = 0; sub < 2; ++sub)
; #pragma unroll
;                 for (int i = 0; i < 16; ++i) { const int kp = k0 + 32 * sub + (i & 3) + 8 * (i >> 2) + 4 * hh; const int dist = qp - kp;
;                     const float v = dist < 0 ? -INFINITY : sc[sub][i] + bdl[dist < 128 ? dist : 128]; sc[sub][i] = v; mx = fmaxf(mx, v); }
;         }
	v_pk_add_f32 v[162:163], v[162:163], v[66:67]
	v_pk_add_f32 v[164:165], v[164:165], v[68:69]
	v_pk_add_f32 v[166:167], v[166:167], v[70:71]
	v_pk_add_f32 v[168:169], v[168:169], v[72:73]
	v_pk_add_f32 v[170:171], v[170:171], v[74:75]
	v_pk_add_f32 v[172:173], v[172:173], v[76:77]
	v_pk_add_f32 v[174:175], v[174:175], v[78:79]
	v_pk_add_f32 v[176:177], v[176:177], v[80:81]
	v_pk_add_f32 v[228:229], v[228:229], v[82:83]
	v_pk_add_f32 v[230:231], v[230:231], v[84:85]
	v_pk_add_f32 v[232:233], v[232:233], v[86:87]
	v_pk_add_f32 v[234:235], v[234:235], v[88:89]
	v_pk_add_f32 v[236:237], v[236:237], v[90:91]
	v_pk_add_f32 v[238:239], v[238:239], v[92:93]
	v_pk_add_f32 v[240:241], v[240:241], v[94:95]
	v_pk_add_f32 v[242:243], v[242:243], v[96:97]
	v_cmp_ge_i32_e64 s[46:47], 59, v145
	v_cmp_ge_i32_e64 s[48:49], 58, v145
	v_cmp_ge_i32_e64 s[50:51], 57, v145
	v_cndmask_b32_e64 v162, v144, v162, s[46:47]
	v_cmp_ge_i32_e64 s[52:53], 56, v145
	v_cndmask_b32_e64 v163, v144, v163, s[48:49]
	v_cmp_ge_i32_e64 s[46:47], 51, v145
	v_cndmask_b32_e64 v164, v144, v164, s[50:51]
	v_cmp_ge_i32_e64 s[48:49], 50, v145
	v_cndmask_b32_e64 v165, v144, v165, s[52:53]
	v_cmp_ge_i32_e64 s[50:51], 49, v145
	v_cndmask_b32_e64 v166, v144, v166, s[46:47]
	v_cmp_ge_i32_e64 s[52:53], 48, v145
	v_cndmask_b32_e64 v167, v144, v167, s[48:49]
	v_cmp_ge_i32_e64 s[46:47], 43, v145
	v_cndmask_b32_e64 v168, v144, v168, s[50:51]
	v_cmp_ge_i32_e64 s[48:49], 42, v145
	v_cndmask_b32_e64 v169, v144, v169, s[52:53]
	v_cmp_ge_i32_e64 s[50:51], 41, v145
	v_cndmask_b32_e64 v170, v144, v170, s[46:47]
	v_cmp_ge_i32_e64 s[52:53], 40, v145
	v_cndmask_b32_e64 v171, v144, v171, s[48:49]
	v_cmp_ge_i32_e64 s[46:47], 35, v145
	v_cndmask_b32_e64 v172, v144, v172, s[50:51]
	v_cmp_ge_i32_e64 s[48:49], 34, v145
	v_cndmask_b32_e64 v173, v144, v173, s[52:53]
	v_cmp_ge_i32_e64 s[50:51], 33, v145
	v_cndmask_b32_e64 v174, v144, v174, s[46:47]
	v_cmp_ge_i32_e64 s[52:53], 32, v145
	v_cndmask_b32_e64 v175, v144, v175, s[48:49]
	v_cmp_ge_i32_e64 s[46:47], 27, v145
	v_cndmask_b32_e64 v176, v144, v176, s[50:51]
	v_cmp_ge_i32_e64 s[48:49], 26, v145
	v_cndmask_b32_e64 v177, v144, v177, s[52:53]
	v_cmp_ge_i32_e64 s[50:51], 25, v145
	v_cndmask_b32_e64 v228, v144, v228, s[46:47]
	v_cmp_ge_i32_e64 s[52:53], 24, v145
	v_cndmask_b32_e64 v229, v144, v229, s[48:49]
	v_cmp_ge_i32_e64 s[46:47], 19, v145
	v_cndmask_b32_e64 v230, v144, v230, s[50:51]
	v_cmp_ge_i32_e64 s[48:49], 18, v145
	v_cndmask_b32_e64 v231, v144, v231, s[52:53]
	v_cmp_ge_i32_e64 s[50:51], 17, v145
	v_cndmask_b32_e64 v232, v144, v232, s[46:47]
	v_cmp_ge_i32_e64 s[52:53], 16, v145
	v_cndmask_b32_e64 v233, v144, v233, s[48:49]
	v_cmp_ge_i32_e64 s[46:47], 11, v145
	v_cndmask_b32_e64 v234, v144, v234, s[50:51]
	v_cmp_ge_i32_e64 s[48:49], 10, v145
	v_cndmask_b32_e64 v235, v144, v235, s[52:53]
	v_cmp_ge_i32_e64 s[50:51], 9, v145
	v_cndmask_b32_e64 v236, v144, v236, s[46:47]
	v_cmp_ge_i32_e64 s[52:53], 8, v145
	v_cndmask_b32_e64 v237, v144, v237, s[48:49]
	v_cmp_ge_i32_e64 s[46:47], 3, v145
	v_cndmask_b32_e64 v238, v144, v238, s[50:51]
	v_cmp_ge_i32_e64 s[48:49], 2, v145
	v_cndmask_b32_e64 v239, v144, v239, s[52:53]
	v_cmp_ge_i32_e64 s[50:51], 1, v145
	v_cndmask_b32_e64 v240, v144, v240, s[46:47]
	v_cmp_ge_i32_e64 s[52:53], 0, v145
	v_cndmask_b32_e64 v241, v144, v241, s[48:49]
	v_cndmask_b32_e64 v242, v144, v242, s[50:51]
	v_cndmask_b32_e64 v243, v144, v243, s[52:53]
	v_mov_b32_e32 v213, 0
	s_branch .LdiffA_max

; __device__ __forceinline__ void diff_attn_item(CParams& p, int j, int layer, LAS unsigned char* lds, int b, int h, int qb, int tid_in, int lane_in, int wave) {
;     ...
;         mx = fmaxf(mx, __shfl_xor(mx, 32));
;         const float m_new = fmaxf(m_run, mx);
;         const float alpha = __builtin_amdgcn_exp2f(m_run - m_new);
;         const bool resc = __ballot(m_new > m_run) != 0ull;
;         float ls = 0.f;
; #pragma unroll
;         for (int sub = 0; sub < 2; ++sub)
; #pragma unroll
;             for (int i = 0; i < 16; ++i) { const float e = __builtin_amdgcn_exp2f(sc[sub][i] - m_new); sc[sub][i] = e; ls += e; }
;         ls += __shfl_xor(ls, 32);
;         l_run = l_run * alpha + ls; m_run = m_new;
.LdiffA_far:
	v_mov_b32_e32 v214, 0x11a00
	ds_read_b32 v213, v214
	s_nop 6
.LdiffA_max:
	s_cmp_eq_u32 s100, 0
	s_cbranch_scc1 .LdiffA_slow
.LdiffA_t:
	s_waitcnt lgkmcnt(0)
	v_sub_f32_e32 v246, v201, v213
	v_pk_add_f32 v[162:163], v[162:163], v[246:247] op_sel_hi:[1,0] neg_lo:[0,1] neg_hi:[0,1]
	v_pk_add_f32 v[164:165], v[164:165], v[246:247] op_sel_hi:[1,0] neg_lo:[0,1] neg_hi:[0,1]
	v_pk_add_f32 v[166:167], v[166:167], v[246:247] op_sel_hi:[1,0] neg_lo:[0,1] neg_hi:[0,1]
	v_pk_add_f32 v[168:169], v[168:169], v[246:247] op_sel_hi:[1,0] neg_lo:[0,1] neg_hi:[0,1]
	v_pk_add_f32 v[170:171], v[170:171], v[246:247] op_sel_hi:[1,0] neg_lo:[0,1] neg_hi:[0,1]
	v_pk_add_f32 v[172:173], v[172:173], v[246:247] op_sel_hi:[1,0] neg_lo:[0,1] neg_hi:[0,1]
	v_pk_add_f32 v[174:175], v[174:175], v[246:247] op_sel_hi:[1,0] neg_lo:[0,1] neg_hi:[0,1]
	v_pk_add_f32 v[176:177], v[176:177], v[246:247] op_sel_hi:[1,0] neg_lo:[0,1] neg_hi:[0,1]
	v_pk_add_f32 v[228:229], v[228:229], v[246:247] op_sel_hi:[1,0] neg_lo:[0,1] neg_hi:[0,1]
	v_pk_add_f32 v[230:231], v[230:231], v[246:247] op_sel_hi:[1,0] neg_lo:[0,1] neg_hi:[0,1]
	v_pk_add_f32 v[232:233], v[232:233], v[246:247] op_sel_hi:[1,0] neg_lo:[0,1] neg_hi:[0,1]
	v_pk_add_f32 v[234:235], v[234:235], v[246:247] op_sel_hi:[1,0] neg_lo:[0,1] neg_hi:[0,1]
	v_pk_add_f32 v[236:237], v[236:237], v[246:247] op_sel_hi:[1,0] neg_lo:[0,1] neg_hi:[0,1]
	v_pk_add_f32 v[238:239], v[238:239], v[246:247] op_sel_hi:[1,0] neg_lo:[0,1] neg_hi:[0,1]
	v_pk_add_f32 v[240:241], v[240:241], v[246:247] op_sel_hi:[1,0] neg_lo:[0,1] neg_hi:[0,1]
	v_pk_add_f32 v[242:243], v[242:243], v[246:247] op_sel_hi:[1,0] neg_lo:[0,1] neg_hi:[0,1]
	v_exp_f32_e32 v162, v162
	v_exp_f32_e32 v163, v163
	v_exp_f32_e32 v164, v164
	v_exp_f32_e32 v165, v165
	v_exp_f32_e32 v166, v166
	v_exp_f32_e32 v167, v167
	v_exp_f32_e32 v168, v168
	v_exp_f32_e32 v169, v169
	v_exp_f32_e32 v170, v170
	v_exp_f32_e32 v171, v171
	v_exp_f32_e32 v172, v172
	v_exp_f32_e32 v173, v173
	v_exp_f32_e32 v174, v174
	v_exp_f32_e32 v175, v175
	v_exp_f32_e32 v176, v176
	v_exp_f32_e32 v177, v177
	v_exp_f32_e32 v228, v228
	v_exp_f32_e32 v229, v229
	v_exp_f32_e32 v230, v230
	v_exp_f32_e32 v231, v231
	v_exp_f32_e32 v232, v232
	v_exp_f32_e32 v233, v233
	v_exp_f32_e32 v234, v234
	v_exp_f32_e32 v235, v235
	v_exp_f32_e32 v236, v236
	v_exp_f32_e32 v237, v237
	v_exp_f32_e32 v238, v238
	v_exp_f32_e32 v239, v239
	v_exp_f32_e32 v240, v240
	v_exp_f32_e32 v241, v241
	v_exp_f32_e32 v242, v242
	v_exp_f32_e32 v243, v243
	v_pk_add_f32 v[250:251], v[162:163], v[164:165]
	v_pk_add_f32 v[250:251], v[250:251], v[166:167]
	v_pk_add_f32 v[250:251], v[250:251], v[168:169]
	v_pk_add_f32 v[250:251], v[250:251], v[170:171]
	v_pk_add_f32 v[250:251], v[250:251], v[172:173]
	v_pk_add_f32 v[250:251], v[250:251], v[174:175]
	v_pk_add_f32 v[250:251], v[250:251], v[176:177]
	v_pk_add_f32 v[250:251], v[250:251], v[228:229]
	v_pk_add_f32 v[250:251], v[250:251], v[230:231]
	v_pk_add_f32 v[250:251], v[250:251], v[232:233]
	v_pk_add_f32 v[250:251], v[250:251], v[234:235]
	v_pk_add_f32 v[250:251], v[250:251], v[236:237]
	v_pk_add_f32 v[250:251], v[250:251], v[238:239]
	v_pk_add_f32 v[250:251], v[250:251], v[240:241]
	v_pk_add_f32 v[250:251], v[250:251], v[242:243]
	s_nop 0
	v_add_f32_e32 v250, v250, v251
	ds_bpermute_b32 v251, v185, v250
	v_cvt_pk_f16_f32 v144, v162, v163
	v_cvt_pk_f16_f32 v145, v164, v165
	v_cvt_pk_f16_f32 v146, v166, v167
	v_cvt_pk_f16_f32 v147, v168, v169
	v_cvt_pk_f16_f32 v148, v170, v171
	v_cvt_pk_f16_f32 v149, v172, v173
	v_cvt_pk_f16_f32 v150, v174, v175
	v_cvt_pk_f16_f32 v151, v176, v177
	v_cvt_pk_f16_f32 v152, v228, v229
	v_cvt_pk_f16_f32 v153, v230, v231
	v_cvt_pk_f16_f32 v154, v232, v233
	v_cvt_pk_f16_f32 v155, v234, v235
	v_cvt_pk_f16_f32 v178, v236, v237
	v_cvt_pk_f16_f32 v179, v238, v239
	v_cvt_pk_f16_f32 v180, v240, v241
	v_cvt_pk_f16_f32 v181, v242, v243
	s_waitcnt lgkmcnt(0)
	v_add_f32_e32 v250, v250, v251
	s_cmp_lg_u32 s101, 0
	s_cbranch_scc1 .LdiffA_ok
	v_cmp_nge_f32_e32 vcc, 0x43800000, v250
	s_cbranch_vccz .LdiffA_ok
	s_mov_b32 s100, 0
	s_mov_b32 s101, 1
	s_branch .LdiffA_top
; #define LAS __attribute__((address_space(3)))
; __device__ __forceinline__ f32x16 mma32(const h16x8 a, const h16x8 b, const f32x16 c) { return __builtin_amdgcn_mfma_f32_32x32x16_f16(a, b, c, 0, 0, 0); }
; __device__ __forceinline__ void diff_attn_item(CParams& p, int j, int layer, LAS unsigned char* lds, int b, int h, int qb, int tid_in, int lane_in, int wave) {
;     ...
;         mx = fmaxf(mx, __shfl_xor(mx, 32));
;         const float m_new = fmaxf(m_run, mx);
;         const float alpha = __builtin_amdgcn_exp2f(m_run - m_new);
;         const bool resc = __ballot(m_new > m_run) != 0ull;
;         float ls = 0.f;
; #pragma unroll
;         for (int sub = 0; sub < 2; ++sub)
; #pragma unroll
;             for (int i = 0; i < 16; ++i) { const float e = __builtin_amdgcn_exp2f(sc[sub][i] - m_new); sc[sub][i] = e; ls += e; }
;         ls += __shfl_xor(ls, 32);
;         l_run = l_run * alpha + ls; m_run = m_new;
;         if (resc) {
; #pragma unroll
;             for (int d = 0; d < 4; ++d)
; #pragma unroll
;                 for (int i = 0; i < 16; ++i) o[d][i] *= alpha;
;         }
; #pragma unroll
;         for (int sub = 0; sub < 2; ++sub)
; #pragma unroll
;             for (int s2 = 0; s2 < 2; ++s2) {
;                 h16x8 pf;
; #pragma unroll
;                 for (int jj = 0; jj < 8; ++jj) pf[jj] = (h16)sc[sub][8 * s2 + jj];
; #pragma unroll
;                 for (int d = 0; d < 4; ++d) {
;                     const int coff = 32 * d * 72 + ((((sub << 1) | s2) ^ d) << 4);
;                     const h16x4 lo = *(const LAS h16x4*)(Vt + vlo + coff), hi = *(const LAS h16x4*)(Vt + vhi + coff);
;                     h16x8 vf; vf[0] = lo[0]; vf[1] = lo[1]; vf[2] = lo[2]; vf[3] = lo[3]; vf[4] = hi[0]; vf[5] = hi[1]; vf[6] = hi[2]; vf[7] = hi[3];
;                     o[d] = mma32(vf, pf, o[d]);
;                 }
;             }
;         }
;         __syncthreads();
;     }
.LdiffA_ok:
	v_add_f32_e32 v197, v197, v250
	ds_read_b128 v[66:69], v215 offset:34816
	ds_read_b128 v[70:73], v215 offset:39456
	ds_read_b128 v[74:77], v215 offset:44096
	ds_read_b128 v[78:81], v215 offset:48736
	ds_read_b128 v[82:85], v215 offset:34848
	ds_read_b128 v[86:89], v215 offset:39424
	ds_read_b128 v[90:93], v215 offset:44128
	ds_read_b128 v[94:97], v215 offset:48704
	s_waitcnt lgkmcnt(4)
	v_mfma_f32_32x32x16_f16 v[50:65], v[66:69], v[144:147], v[50:65]
	v_mfma_f32_32x32x16_f16 v[34:49], v[70:73], v[144:147], v[34:49]
	v_mfma_f32_32x32x16_f16 v[18:33], v[74:77], v[144:147], v[18:33]
	v_mfma_f32_32x32x16_f16 v[2:17], v[78:81], v[144:147], v[2:17]
	ds_read_b128 v[66:69], v215 offset:34880
	ds_read_b128 v[70:73], v215 offset:39520
	ds_read_b128 v[74:77], v215 offset:44032
	ds_read_b128 v[78:81], v215 offset:48672
	s_waitcnt lgkmcnt(4)
	v_mfma_f32_32x32x16_f16 v[50:65], v[82:85], v[148:151], v[50:65]
	v_mfma_f32_32x32x16_f16 v[34:49], v[86:89], v[148:151], v[34:49]
	v_mfma_f32_32x32x16_f16 v[18:33], v[90:93], v[148:151], v[18:33]
	v_mfma_f32_32x32x16_f16 v[2:17], v[94:97], v[148:151], v[2:17]
	ds_read_b128 v[82:85], v215 offset:34912
	ds_read_b128 v[86:89], v215 offset:39488
	ds_read_b128 v[90:93], v215 offset:44064
	ds_read_b128 v[94:97], v215 offset:48640
	s_waitcnt lgkmcnt(4)
	v_mfma_f32_32x32x16_f16 v[50:65], v[66:69], v[152:155], v[50:65]
	v_mfma_f32_32x32x16_f16 v[34:49], v[70:73], v[152:155], v[34:49]
	v_mfma_f32_32x32x16_f16 v[18:33], v[74:77], v[152:155], v[18:33]
	v_mfma_f32_32x32x16_f16 v[2:17], v[78:81], v[152:155], v[2:17]
	s_waitcnt lgkmcnt(0)
	v_mfma_f32_32x32x16_f16 v[50:65], v[82:85], v[178:181], v[50:65]
	v_mfma_f32_32x32x16_f16 v[34:49], v[86:89], v[178:181], v[34:49]
	v_mfma_f32_32x32x16_f16 v[18:33], v[90:93], v[178:181], v[18:33]
	v_mfma_f32_32x32x16_f16 v[2:17], v[94:97], v[178:181], v[2:17]
	s_branch .LdiffA_end
.LdiffA_slow:
	v_max3_f32 v249, v162, v163, v164
	v_max3_f32 v249, v249, v165, v166
	v_max3_f32 v249, v249, v167, v168
	v_max3_f32 v249, v249, v169, v170
	v_max3_f32 v249, v249, v171, v172
	v_max3_f32 v249, v249, v173, v174
	v_max3_f32 v249, v249, v175, v176
	v_max3_f32 v249, v249, v177, v228
	v_max3_f32 v249, v249, v229, v230
	v_max3_f32 v249, v249, v231, v232
	v_max3_f32 v249, v249, v233, v234
	v_max3_f32 v249, v249, v235, v236
	v_max3_f32 v249, v249, v237, v238
	v_max3_f32 v249, v249, v239, v240
	v_max3_f32 v249, v249, v241, v242
	v_max_f32_e32 v249, v249, v243
	s_waitcnt lgkmcnt(0)
	v_add_f32_e32 v249, v249, v213
	ds_bpermute_b32 v251, v185, v249
	s_waitcnt lgkmcnt(0)
	v_max3_f32 v248, v201, v249, v251
	v_sub_f32_e32 v244, v201, v248
	v_exp_f32_e32 v244, v244
	v_cmp_gt_f32_e32 vcc, v248, v201
	v_mov_b32_e32 v201, v248
	s_cbranch_vccz .LdiffA_nomove
	v_mul_f32_e32 v197, v197, v244
	v_pk_mul_f32 v[50:51], v[50:51], v[244:245] op_sel_hi:[1,0]
	v_pk_mul_f32 v[52:53], v[52:53], v[244:245] op_sel_hi:[1,0]
	v_pk_mul_f32 v[54:55], v[54:55], v[244:245] op_sel_hi:[1,0]
	v_pk_mul_f32 v[56:57], v[56:57], v[244:245] op_sel_hi:[1,0]
	v_pk_mul_f32 v[58:59], v[58:59], v[244:245] op_sel_hi:[1,0]
	v_pk_mul_f32 v[60:61], v[60:61], v[244:245] op_sel_hi:[1,0]
	v_pk_mul_f32 v[62:63], v[62:63], v[244:245] op_sel_hi:[1,0]
	v_pk_mul_f32 v[64:65], v[64:65], v[244:245] op_sel_hi:[1,0]
	v_pk_mul_f32 v[34:35], v[34:35], v[244:245] op_sel_hi:[1,0]
	v_pk_mul_f32 v[36:37], v[36:37], v[244:245] op_sel_hi:[1,0]
	v_pk_mul_f32 v[38:39], v[38:39], v[244:245] op_sel_hi:[1,0]
	v_pk_mul_f32 v[40:41], v[40:41], v[244:245] op_sel_hi:[1,0]
	v_pk_mul_f32 v[42:43], v[42:43], v[244:245] op_sel_hi:[1,0]
	v_pk_mul_f32 v[44:45], v[44:45], v[244:245] op_sel_hi:[1,0]
	v_pk_mul_f32 v[46:47], v[46:47], v[244:245] op_sel_hi:[1,0]
	v_pk_mul_f32 v[48:49], v[48:49], v[244:245] op_sel_hi:[1,0]
	v_pk_mul_f32 v[18:19], v[18:19], v[244:245] op_sel_hi:[1,0]
	v_pk_mul_f32 v[20:21], v[20:21], v[244:245] op_sel_hi:[1,0]
	v_pk_mul_f32 v[22:23], v[22:23], v[244:245] op_sel_hi:[1,0]
	v_pk_mul_f32 v[24:25], v[24:25], v[244:245] op_sel_hi:[1,0]
	v_pk_mul_f32 v[26:27], v[26:27], v[244:245] op_sel_hi:[1,0]
	v_pk_mul_f32 v[28:29], v[28:29], v[244:245] op_sel_hi:[1,0]
	v_pk_mul_f32 v[30:31], v[30:31], v[244:245] op_sel_hi:[1,0]
	v_pk_mul_f32 v[32:33], v[32:33], v[244:245] op_sel_hi:[1,0]
	v_pk_mul_f32 v[2:3], v[2:3], v[244:245] op_sel_hi:[1,0]
	v_pk_mul_f32 v[4:5], v[4:5], v[244:245] op_sel_hi:[1,0]
	v_pk_mul_f32 v[6:7], v[6:7], v[244:245] op_sel_hi:[1,0]
	v_pk_mul_f32 v[8:9], v[8:9], v[244:245] op_sel_hi:[1,0]
	v_pk_mul_f32 v[10:11], v[10:11], v[244:245] op_sel_hi:[1,0]
	v_pk_mul_f32 v[12:13], v[12:13], v[244:245] op_sel_hi:[1,0]
	v_pk_mul_f32 v[14:15], v[14:15], v[244:245] op_sel_hi:[1,0]
	v_pk_mul_f32 v[16:17], v[16:17], v[244:245] op_sel_hi:[1,0]
.LdiffA_nomove:
	v_cmp_neq_f32_e32 vcc, 0xff800000, v201
	s_cmp_eq_u64 vcc, exec
	s_cselect_b32 s100, 1, 0
	s_branch .LdiffA_t
.LdiffA_end:
.LBB0_670:
	s_or_b64 exec, exec, s[4:5]
	s_add_i32 s12, s38, 1
	s_add_i32 s40, s40, 64
	s_cmp_eq_u32 s38, s37
	v_subrev_u32_e32 v212, 64, v212
	s_waitcnt lgkmcnt(0)
	s_barrier
	s_cbranch_scc1 .LBB0_672
	s_mov_b32 s38, s12
	s_branch .LBB0_598
.LBB0_672:
	s_lshl_b32 s30, s12, 6
	v_cmp_le_u32_e32 vcc, s30, v210
	s_and_saveexec_b64 s[4:5], vcc
	s_cbranch_execz .LBB0_744
	s_and_b32 s41, s12, 1
	s_waitcnt vmcnt(0)
	s_mov_b32 s101, 0

; __device__ __forceinline__ void diff_attn_item(CParams& p, int j, int layer, LAS unsigned char* lds, int b, int h, int qb, int tid_in, int lane_in, int wave) {
;     ...
;         float mx = -INFINITY;
;         if (k0 + 63 + 128 <= q0) {
;             const float bfar = bdl[128];
; #pragma unroll
;             for (int sub = 0; sub < 2; ++sub)
; #pragma unroll
;                 for (int i = 0; i < 16; ++i) { sc[sub][i] += bfar; mx = fmaxf(mx, sc[sub][i]); }
;         } else {
; #pragma unroll
;             for (int sub = 0; sub < 2; ++sub)
; #pragma unroll
;                 for (int i = 0; i < 16; ++i) { const int kp = k0 + 32 * sub + (i & 3) + 8 * (i >> 2) + 4 * hh; const int dist = qp - kp;
;                     const float v = dist < 0 ? -INFINITY : sc[sub][i] + bdl[dist < 128 ? dist : 128]; sc[sub][i] = v; mx = fmaxf(mx, v); }
;         }
;         mx = fmaxf(mx, __shfl_xor(mx, 32));
;         const float m_new = fmaxf(m_run, mx);
;         const float alpha = __builtin_amdgcn_exp2f(m_run - m_new);
;         const bool resc = __ballot(m_new > m_run) != 0ull;
.LdiffB_far:
	v_mov_b32_e32 v214, 0x11a00
	ds_read_b32 v213, v214
	s_nop 6
.LdiffB_max:
	s_cmp_eq_u32 s100, 0
	s_cbranch_scc1 .LdiffB_slow

; __device__ __forceinline__ void diff_attn_item(CParams& p, int j, int layer, LAS unsigned char* lds, int b, int h, int qb, int tid_in, int lane_in, int wave) {
;     ...
;     const float inv = 1.f / l_run;
;     if (mp == 1) {
; #pragma unroll
;         for (int d = 0; d < 4; ++d)
; #pragma unroll
;             for (int i = 0; i < 16; ++i) Ox[(qs * 64 + d * 16 + i) * 64 + lane] = o[d][i] * inv;
;     }
;     __syncthreads();
.LdiffB_end:
.LBB0_744:
	s_or_b64 exec, exec, s[4:5]
	v_div_scale_f32 v66, s[4:5], v197, v197, 1.0
	v_rcp_f32_e32 v67, v66
	s_barrier
	v_fma_f32 v68, -v66, v67, 1.0
	v_fmac_f32_e32 v67, v68, v67
	v_div_scale_f32 v68, vcc, 1.0, v197, 1.0
	v_mul_f32_e32 v69, v68, v67
	v_fma_f32 v70, -v66, v69, v68
	v_fmac_f32_e32 v69, v70, v67
	v_fma_f32 v66, -v66, v69, v68
	v_div_fmas_f32 v66, v66, v67, v69
	v_div_fixup_f32 v68, v66, v197, 1.0
	s_and_saveexec_b64 s[4:5], s[8:9]
	s_cbranch_execz .LBB0_746
	v_mul_f32_e32 v66, v50, v68
	v_lshl_add_u32 v67, v193, 2, v188
	v_mul_f32_e32 v69, v51, v68
	ds_write2st64_b32 v67, v66, v69 offset1:1
	v_mul_f32_e32 v66, v52, v68
	v_mul_f32_e32 v69, v53, v68
	ds_write2st64_b32 v67, v66, v69 offset0:2 offset1:3
	v_mul_f32_e32 v66, v54, v68
	v_mul_f32_e32 v69, v55, v68
	ds_write2st64_b32 v67, v66, v69 offset0:4 offset1:5
	v_mul_f32_e32 v66, v56, v68
	v_mul_f32_e32 v69, v57, v68
	ds_write2st64_b32 v67, v66, v69 offset0:6 offset1:7
	v_mul_f32_e32 v66, v58, v68
	v_mul_f32_e32 v69, v59, v68
	ds_write2st64_b32 v67, v66, v69 offset0:8 offset1:9
	v_mul_f32_e32 v66, v60, v68
	v_mul_f32_e32 v69, v61, v68
	ds_write2st64_b32 v67, v66, v69 offset0:10 offset1:11
	v_mul_f32_e32 v66, v62, v68
	v_mul_f32_e32 v69, v63, v68
	ds_write2st64_b32 v67, v66, v69 offset0:12 offset1:13
	v_mul_f32_e32 v66, v64, v68
	v_mul_f32_e32 v69, v65, v68
	ds_write2st64_b32 v67, v66, v69 offset0:14 offset1:15
	v_mul_f32_e32 v66, v34, v68
	v_mul_f32_e32 v69, v35, v68
	ds_write2st64_b32 v67, v66, v69 offset0:16 offset1:17
	v_mul_f32_e32 v66, v36, v68
	v_mul_f32_e32 v69, v37, v68
	ds_write2st64_b32 v67, v66, v69 offset0:18 offset1:19
	v_mul_f32_e32 v66, v38, v68
	v_mul_f32_e32 v69, v39, v68
	ds_write2st64_b32 v67, v66, v69 offset0:20 offset1:21
	v_mul_f32_e32 v66, v40, v68
	v_mul_f32_e32 v69, v41, v68
	ds_write2st64_b32 v67, v66, v69 offset0:22 offset1:23
	v_mul_f32_e32 v66, v42, v68
	v_mul_f32_e32 v69, v43, v68
	ds_write2st64_b32 v67, v66, v69 offset0:24 offset1:25
	v_mul_f32_e32 v66, v44, v68
	v_mul_f32_e32 v69, v45, v68
	ds_write2st64_b32 v67, v66, v69 offset0:26 offset1:27
	v_mul_f32_e32 v66, v46, v68
	v_mul_f32_e32 v69, v47, v68
	ds_write2st64_b32 v67, v66, v69 offset0:28 offset1:29
	v_mul_f32_e32 v66, v48, v68
	v_mul_f32_e32 v69, v49, v68
	ds_write2st64_b32 v67, v66, v69 offset0:30 offset1:31
	v_mul_f32_e32 v66, v18, v68
	v_mul_f32_e32 v69, v19, v68
	ds_write2st64_b32 v67, v66, v69 offset0:32 offset1:33
	v_mul_f32_e32 v66, v20, v68
	v_mul_f32_e32 v69, v21, v68
	ds_write2st64_b32 v67, v66, v69 offset0:34 offset1:35
	v_mul_f32_e32 v66, v22, v68
	v_mul_f32_e32 v69, v23, v68
	ds_write2st64_b32 v67, v66, v69 offset0:36 offset1:37
	v_mul_f32_e32 v66, v24, v68
	v_mul_f32_e32 v69, v25, v68
	ds_write2st64_b32 v67, v66, v69 offset0:38 offset1:39
	v_mul_f32_e32 v66, v26, v68
	v_mul_f32_e32 v69, v27, v68
	ds_write2st64_b32 v67, v66, v69 offset0:40 offset1:41
	v_mul_f32_e32 v66, v28, v68
	v_mul_f32_e32 v69, v29, v68
	ds_write2st64_b32 v67, v66, v69 offset0:42 offset1:43
	v_mul_f32_e32 v66, v30, v68
	v_mul_f32_e32 v69, v31, v68
	ds_write2st64_b32 v67, v66, v69 offset0:44 offset1:45
	v_mul_f32_e32 v66, v32, v68
	v_mul_f32_e32 v69, v33, v68
	ds_write2st64_b32 v67, v66, v69 offset0:46 offset1:47
	v_mul_f32_e32 v66, v2, v68
	v_mul_f32_e32 v69, v3, v68
	ds_write2st64_b32 v67, v66, v69 offset0:48 offset1:49
	v_mul_f32_e32 v66, v4, v68
	v_mul_f32_e32 v69, v5, v68
	ds_write2st64_b32 v67, v66, v69 offset0:50 offset1:51
	v_mul_f32_e32 v66, v6, v68
	v_mul_f32_e32 v69, v7, v68
	ds_write2st64_b32 v67, v66, v69 offset0:52 offset1:53
	v_mul_f32_e32 v66, v8, v68
	v_mul_f32_e32 v69, v9, v68
	ds_write2st64_b32 v67, v66, v69 offset0:54 offset1:55
	v_mul_f32_e32 v66, v10, v68
	v_mul_f32_e32 v69, v11, v68
	ds_write2st64_b32 v67, v66, v69 offset0:56 offset1:57
	v_mul_f32_e32 v66, v12, v68
	v_mul_f32_e32 v69, v13, v68
	ds_write2st64_b32 v67, v66, v69 offset0:58 offset1:59
	v_mul_f32_e32 v66, v14, v68
	v_mul_f32_e32 v69, v15, v68
	ds_write2st64_b32 v67, v66, v69 offset0:60 offset1:61
	v_mul_f32_e32 v66, v16, v68
	v_mul_f32_e32 v69, v17, v68
	ds_write2st64_b32 v67, v66, v69 offset0:62 offset1:63
